# grid barriers: no s_sleep between polls of the TOP arrival counter (tight polling)
# baseline (speedup 1.0000x reference)
.LBB0_153:
	s_and_b32 s15, s14, 0xff
	s_mov_b64 s[46:47], -1
	s_cmp_lg_u32 s15, 0
	s_mov_b64 s[52:53], -1
	s_cbranch_scc1 .LBB0_156
	global_load_dword v2, v0, s[12:13] sc1
	s_waitcnt vmcnt(0)
	v_cmp_eq_u32_e32 vcc, 0, v2
	s_cbranch_vccnz .LBB0_158
	s_mov_b64 s[52:53], 0
	s_mov_b64 s[48:49], -1

.LBB0_170:
	s_and_b32 s15, s14, 0xff
	s_cmp_lg_u32 s15, 0
	s_mov_b64 s[48:49], -1
	s_cbranch_scc1 .LBB0_173
	global_load_dword v1, v0, s[12:13] sc1
	s_waitcnt vmcnt(0)
	v_cmp_eq_u32_e32 vcc, 0, v1
	s_cbranch_vccnz .LBB0_175
	s_mov_b64 s[48:49], 0
	s_mov_b64 s[46:47], -1

.LBB0_246:
	s_and_b32 s15, s14, 0xff
	s_mov_b64 s[28:29], -1
	s_cmp_lg_u32 s15, 0
	s_mov_b64 s[48:49], -1
	s_cbranch_scc1 .LBB0_249
	global_load_dword v2, v0, s[10:11] sc1
	s_waitcnt vmcnt(0)
	v_cmp_eq_u32_e32 vcc, 0, v2
	s_cbranch_vccnz .LBB0_251
	s_mov_b64 s[48:49], 0
	s_mov_b64 s[46:47], -1

.LBB0_263:
	s_and_b32 s15, s14, 0xff
	s_cmp_lg_u32 s15, 0
	s_mov_b64 s[46:47], -1
	s_cbranch_scc1 .LBB0_266
	global_load_dword v1, v0, s[10:11] sc1
	s_waitcnt vmcnt(0)
	v_cmp_eq_u32_e32 vcc, 0, v1
	s_cbranch_vccnz .LBB0_268
	s_mov_b64 s[46:47], 0
	s_mov_b64 s[28:29], -1

.LBB0_313:
	s_and_b32 s15, s14, 0xff
	s_mov_b64 s[24:25], -1
	s_cmp_lg_u32 s15, 0
	s_mov_b64 s[28:29], -1
	s_cbranch_scc1 .LBB0_316
	global_load_dword v2, v0, s[12:13] sc1
	s_waitcnt vmcnt(0)
	v_cmp_eq_u32_e32 vcc, 0, v2
	s_cbranch_vccnz .LBB0_318
	s_mov_b64 s[28:29], 0
	s_mov_b64 s[26:27], -1

.LBB0_330:
	s_and_b32 s15, s14, 0xff
	s_cmp_lg_u32 s15, 0
	s_mov_b64 s[26:27], -1
	s_cbranch_scc1 .LBB0_333
	global_load_dword v1, v0, s[12:13] sc1
	s_waitcnt vmcnt(0)
	v_cmp_eq_u32_e32 vcc, 0, v1
	s_cbranch_vccnz .LBB0_335
	s_mov_b64 s[26:27], 0
	s_mov_b64 s[24:25], -1

.LBB0_789:
	s_and_b32 s24, s3, 0xff
	s_mov_b64 s[22:23], -1
	s_cmp_lg_u32 s24, 0
	s_mov_b64 s[26:27], -1
	s_cbranch_scc1 .LBB0_792
	global_load_dword v2, v0, s[12:13] sc1
	s_waitcnt vmcnt(0)
	v_cmp_eq_u32_e32 vcc, 0, v2
	s_cbranch_vccnz .LBB0_794
	s_mov_b64 s[26:27], 0
	s_mov_b64 s[24:25], -1

.LBB0_806:
	s_and_b32 s22, s3, 0xff
	s_cmp_lg_u32 s22, 0
	s_mov_b64 s[24:25], -1
	s_cbranch_scc1 .LBB0_809
	global_load_dword v1, v0, s[12:13] sc1
	s_waitcnt vmcnt(0)
	v_cmp_eq_u32_e32 vcc, 0, v1
	s_cbranch_vccnz .LBB0_811
	s_mov_b64 s[24:25], 0
	s_mov_b64 s[22:23], -1
